# strategy 2 (epilogue de-serialisation): P8 gated-merge epilogues rewritten - gate/Y1 loads issued up front or with 7-group look-ahead and counted vmcnt instead of a 16-step load/vmcnt(0)/store ladder
# speedup vs baseline: 1.0065x; 1.0010x over previous
.LBB0_1487:
	s_ashr_i32 s47, s46, 31
	s_lshl_b64 s[46:47], s[46:47], 8
	v_mov_b32_e32 v144, v148
	v_mov_b32_e32 v169, v149
	s_add_u32 s46, s46, s69
	s_addc_u32 s47, s47, s72
	v_ashrrev_i32_e32 v145, 31, v144
	v_lshl_add_u64 v[146:147], s[46:47], 0, v[144:145]
	s_lshl_b32 s46, s82, 8
	s_or_b32 s46, s46, s70
	v_lshl_add_u32 v144, v169, 3, s46
	v_lshlrev_b64 v[170:171], 12, v[146:147]
	v_ashrrev_i32_e32 v145, 31, v144
	v_lshl_add_u64 v[170:171], s[8:9], 0, v[170:171]
	v_lshlrev_b64 v[144:145], 1, v[144:145]
	v_lshl_add_u64 v[174:175], v[170:171], 0, v[144:145]
	v_lshlrev_b64 v[176:177], 11, v[146:147]
	v_lshl_add_u64 v[176:177], s[86:87], 0, v[176:177]
	v_lshl_add_u64 v[176:177], v[176:177], 0, v[144:145]
	s_mov_b64 s[46:47], 0x90
	s_and_b64 vcc, exec, s[6:7]
	s_mov_b64 s[6:7], -1
	v_mov_b32_e32 v170, v174
	v_mov_b32_e32 v171, v175
	v_mov_b32_e32 v172, v176
	v_mov_b32_e32 v173, v177
	s_mov_b32 s101, 0
	global_load_dwordx4 v[184:187], v[170:171], off
	global_load_dwordx4 v[188:191], v[170:171], off offset:256
	s_mov_b32 s100, 0x10000
	v_lshl_add_u64 v[174:175], v[170:171], 0, s[100:101]
	global_load_dwordx4 v[192:195], v[174:175], off
	s_mov_b32 s100, 0x10000
	v_lshl_add_u64 v[174:175], v[170:171], 0, s[100:101]
	global_load_dwordx4 v[196:199], v[174:175], off offset:256
	s_mov_b32 s100, 0x20000
	v_lshl_add_u64 v[174:175], v[170:171], 0, s[100:101]
	global_load_dwordx4 v[200:203], v[174:175], off
	s_mov_b32 s100, 0x20000
	v_lshl_add_u64 v[174:175], v[170:171], 0, s[100:101]
	global_load_dwordx4 v[204:207], v[174:175], off offset:256
	s_mov_b32 s100, 0x30000
	v_lshl_add_u64 v[174:175], v[170:171], 0, s[100:101]
	global_load_dwordx4 v[208:211], v[174:175], off
	s_mov_b32 s100, 0x30000
	v_lshl_add_u64 v[174:175], v[170:171], 0, s[100:101]
	global_load_dwordx4 v[212:215], v[174:175], off offset:256
	s_mov_b32 s100, 0x80000
	v_lshl_add_u64 v[174:175], v[170:171], 0, s[100:101]
	global_load_dwordx4 v[216:219], v[174:175], off
	s_mov_b32 s100, 0x80000
	v_lshl_add_u64 v[174:175], v[170:171], 0, s[100:101]
	global_load_dwordx4 v[220:223], v[174:175], off offset:256
	s_mov_b32 s100, 0x90000
	v_lshl_add_u64 v[174:175], v[170:171], 0, s[100:101]
	global_load_dwordx4 v[224:227], v[174:175], off
	s_mov_b32 s100, 0x90000
	v_lshl_add_u64 v[174:175], v[170:171], 0, s[100:101]
	global_load_dwordx4 v[228:231], v[174:175], off offset:256
	s_mov_b32 s100, 0xa0000
	v_lshl_add_u64 v[174:175], v[170:171], 0, s[100:101]
	global_load_dwordx4 v[232:235], v[174:175], off
	s_mov_b32 s100, 0xa0000
	v_lshl_add_u64 v[174:175], v[170:171], 0, s[100:101]
	global_load_dwordx4 v[236:239], v[174:175], off offset:256
	s_mov_b32 s100, 0xb0000
	v_lshl_add_u64 v[174:175], v[170:171], 0, s[100:101]
	global_load_dwordx4 v[240:243], v[174:175], off
	s_waitcnt vmcnt(14)
	v_lshlrev_b32_e32 v180, 16, v184
	v_and_b32_e32 v181, 0xffff0000, v184
	v_lshlrev_b32_e32 v184, 16, v185
	v_and_b32_e32 v185, 0xffff0000, v185
	v_lshlrev_b32_e32 v182, 16, v186
	v_and_b32_e32 v183, 0xffff0000, v186
	v_lshlrev_b32_e32 v186, 16, v187
	v_and_b32_e32 v187, 0xffff0000, v187
	v_pk_mul_f32 v[124:125], v[124:125], v[180:181]
	v_pk_mul_f32 v[126:127], v[126:127], v[184:185]
	v_pk_mul_f32 v[182:183], v[120:121], v[182:183]
	v_pk_mul_f32 v[186:187], v[122:123], v[186:187]
	v_cvt_pk_bf16_f32 v120, v124, v125
	v_cvt_pk_bf16_f32 v121, v126, v127
	v_cvt_pk_bf16_f32 v122, v182, v183
	v_cvt_pk_bf16_f32 v123, v186, v187
	global_store_dwordx4 v[172:173], v[120:123], off
	s_mov_b32 s100, 0xb0000
	v_lshl_add_u64 v[174:175], v[170:171], 0, s[100:101]
	global_load_dwordx4 v[184:187], v[174:175], off offset:256
	s_waitcnt vmcnt(15)
	v_lshlrev_b32_e32 v180, 16, v188
	v_and_b32_e32 v181, 0xffff0000, v188
	v_lshlrev_b32_e32 v188, 16, v189
	v_and_b32_e32 v189, 0xffff0000, v189
	v_lshlrev_b32_e32 v182, 16, v190
	v_and_b32_e32 v183, 0xffff0000, v190
	v_lshlrev_b32_e32 v190, 16, v191
	v_and_b32_e32 v191, 0xffff0000, v191
	v_pk_mul_f32 v[116:117], v[116:117], v[180:181]
	v_pk_mul_f32 v[118:119], v[118:119], v[188:189]
	v_pk_mul_f32 v[182:183], v[112:113], v[182:183]
	v_pk_mul_f32 v[190:191], v[114:115], v[190:191]
	v_cvt_pk_bf16_f32 v112, v116, v117
	v_cvt_pk_bf16_f32 v113, v118, v119
	v_cvt_pk_bf16_f32 v114, v182, v183
	v_cvt_pk_bf16_f32 v115, v190, v191
	global_store_dwordx4 v[172:173], v[112:115], off offset:256
	s_waitcnt vmcnt(15)
	v_lshlrev_b32_e32 v180, 16, v192
	v_and_b32_e32 v181, 0xffff0000, v192
	v_lshlrev_b32_e32 v192, 16, v193
	v_and_b32_e32 v193, 0xffff0000, v193
	v_lshlrev_b32_e32 v182, 16, v194
	v_and_b32_e32 v183, 0xffff0000, v194
	v_lshlrev_b32_e32 v194, 16, v195
	v_and_b32_e32 v195, 0xffff0000, v195
	v_pk_mul_f32 v[108:109], v[108:109], v[180:181]
	v_pk_mul_f32 v[110:111], v[110:111], v[192:193]
	v_pk_mul_f32 v[182:183], v[104:105], v[182:183]
	v_pk_mul_f32 v[194:195], v[106:107], v[194:195]
	v_cvt_pk_bf16_f32 v104, v108, v109
	v_cvt_pk_bf16_f32 v105, v110, v111
	v_cvt_pk_bf16_f32 v106, v182, v183
	v_cvt_pk_bf16_f32 v107, v194, v195
	s_mov_b32 s100, 0x8000
	v_lshl_add_u64 v[178:179], v[172:173], 0, s[100:101]
	global_store_dwordx4 v[178:179], v[104:107], off
	s_waitcnt vmcnt(15)
	v_lshlrev_b32_e32 v180, 16, v196
	v_and_b32_e32 v181, 0xffff0000, v196
	v_lshlrev_b32_e32 v196, 16, v197
	v_and_b32_e32 v197, 0xffff0000, v197
	v_lshlrev_b32_e32 v182, 16, v198
	v_and_b32_e32 v183, 0xffff0000, v198
	v_lshlrev_b32_e32 v198, 16, v199
	v_and_b32_e32 v199, 0xffff0000, v199
	v_pk_mul_f32 v[100:101], v[100:101], v[180:181]
	v_pk_mul_f32 v[102:103], v[102:103], v[196:197]
	v_pk_mul_f32 v[182:183], v[96:97], v[182:183]
	v_pk_mul_f32 v[198:199], v[98:99], v[198:199]
	v_cvt_pk_bf16_f32 v96, v100, v101
	v_cvt_pk_bf16_f32 v97, v102, v103
	v_cvt_pk_bf16_f32 v98, v182, v183
	v_cvt_pk_bf16_f32 v99, v198, v199
	global_store_dwordx4 v[178:179], v[96:99], off offset:256
	s_waitcnt vmcnt(15)
	v_lshlrev_b32_e32 v180, 16, v200
	v_and_b32_e32 v181, 0xffff0000, v200
	v_lshlrev_b32_e32 v200, 16, v201
	v_and_b32_e32 v201, 0xffff0000, v201
	v_lshlrev_b32_e32 v182, 16, v202
	v_and_b32_e32 v183, 0xffff0000, v202
	v_lshlrev_b32_e32 v202, 16, v203
	v_and_b32_e32 v203, 0xffff0000, v203
	v_pk_mul_f32 v[92:93], v[92:93], v[180:181]
	v_pk_mul_f32 v[94:95], v[94:95], v[200:201]
	v_pk_mul_f32 v[182:183], v[88:89], v[182:183]
	v_pk_mul_f32 v[202:203], v[90:91], v[202:203]
	v_cvt_pk_bf16_f32 v88, v92, v93
	v_cvt_pk_bf16_f32 v89, v94, v95
	v_cvt_pk_bf16_f32 v90, v182, v183
	v_cvt_pk_bf16_f32 v91, v202, v203
	s_mov_b32 s100, 0x10000
	v_lshl_add_u64 v[178:179], v[172:173], 0, s[100:101]
	global_store_dwordx4 v[178:179], v[88:91], off
	s_waitcnt vmcnt(15)
	v_lshlrev_b32_e32 v180, 16, v204
	v_and_b32_e32 v181, 0xffff0000, v204
	v_lshlrev_b32_e32 v204, 16, v205
	v_and_b32_e32 v205, 0xffff0000, v205
	v_lshlrev_b32_e32 v182, 16, v206
	v_and_b32_e32 v183, 0xffff0000, v206
	v_lshlrev_b32_e32 v206, 16, v207
	v_and_b32_e32 v207, 0xffff0000, v207
	v_pk_mul_f32 v[84:85], v[84:85], v[180:181]
	v_pk_mul_f32 v[86:87], v[86:87], v[204:205]
	v_pk_mul_f32 v[182:183], v[80:81], v[182:183]
	v_pk_mul_f32 v[206:207], v[82:83], v[206:207]
	v_cvt_pk_bf16_f32 v80, v84, v85
	v_cvt_pk_bf16_f32 v81, v86, v87
	v_cvt_pk_bf16_f32 v82, v182, v183
	v_cvt_pk_bf16_f32 v83, v206, v207
	global_store_dwordx4 v[178:179], v[80:83], off offset:256
	s_waitcnt vmcnt(15)
	v_lshlrev_b32_e32 v180, 16, v208
	v_and_b32_e32 v181, 0xffff0000, v208
	v_lshlrev_b32_e32 v208, 16, v209
	v_and_b32_e32 v209, 0xffff0000, v209
	v_lshlrev_b32_e32 v182, 16, v210
	v_and_b32_e32 v183, 0xffff0000, v210
	v_lshlrev_b32_e32 v210, 16, v211
	v_and_b32_e32 v211, 0xffff0000, v211
	v_pk_mul_f32 v[76:77], v[76:77], v[180:181]
	v_pk_mul_f32 v[78:79], v[78:79], v[208:209]
	v_pk_mul_f32 v[182:183], v[72:73], v[182:183]
	v_pk_mul_f32 v[210:211], v[74:75], v[210:211]
	v_cvt_pk_bf16_f32 v72, v76, v77
	v_cvt_pk_bf16_f32 v73, v78, v79
	v_cvt_pk_bf16_f32 v74, v182, v183
	v_cvt_pk_bf16_f32 v75, v210, v211
	s_mov_b32 s100, 0x18000
	v_lshl_add_u64 v[178:179], v[172:173], 0, s[100:101]
	global_store_dwordx4 v[178:179], v[72:75], off
	s_waitcnt vmcnt(15)
	v_lshlrev_b32_e32 v180, 16, v212
	v_and_b32_e32 v181, 0xffff0000, v212
	v_lshlrev_b32_e32 v212, 16, v213
	v_and_b32_e32 v213, 0xffff0000, v213
	v_lshlrev_b32_e32 v182, 16, v214
	v_and_b32_e32 v183, 0xffff0000, v214
	v_lshlrev_b32_e32 v214, 16, v215
	v_and_b32_e32 v215, 0xffff0000, v215
	v_pk_mul_f32 v[68:69], v[68:69], v[180:181]
	v_pk_mul_f32 v[70:71], v[70:71], v[212:213]
	v_pk_mul_f32 v[182:183], v[64:65], v[182:183]
	v_pk_mul_f32 v[214:215], v[66:67], v[214:215]
	v_cvt_pk_bf16_f32 v64, v68, v69
	v_cvt_pk_bf16_f32 v65, v70, v71
	v_cvt_pk_bf16_f32 v66, v182, v183
	v_cvt_pk_bf16_f32 v67, v214, v215
	global_store_dwordx4 v[178:179], v[64:67], off offset:256
	s_waitcnt vmcnt(15)
	v_lshlrev_b32_e32 v180, 16, v216
	v_and_b32_e32 v181, 0xffff0000, v216
	v_lshlrev_b32_e32 v216, 16, v217
	v_and_b32_e32 v217, 0xffff0000, v217
	v_lshlrev_b32_e32 v182, 16, v218
	v_and_b32_e32 v183, 0xffff0000, v218
	v_lshlrev_b32_e32 v218, 16, v219
	v_and_b32_e32 v219, 0xffff0000, v219
	v_pk_mul_f32 v[60:61], v[60:61], v[180:181]
	v_pk_mul_f32 v[62:63], v[62:63], v[216:217]
	v_pk_mul_f32 v[182:183], v[56:57], v[182:183]
	v_pk_mul_f32 v[218:219], v[58:59], v[218:219]
	v_cvt_pk_bf16_f32 v56, v60, v61
	v_cvt_pk_bf16_f32 v57, v62, v63
	v_cvt_pk_bf16_f32 v58, v182, v183
	v_cvt_pk_bf16_f32 v59, v218, v219
	s_mov_b32 s100, 0x40000
	v_lshl_add_u64 v[178:179], v[172:173], 0, s[100:101]
	global_store_dwordx4 v[178:179], v[56:59], off
	s_waitcnt vmcnt(15)
	v_lshlrev_b32_e32 v180, 16, v220
	v_and_b32_e32 v181, 0xffff0000, v220
	v_lshlrev_b32_e32 v220, 16, v221
	v_and_b32_e32 v221, 0xffff0000, v221
	v_lshlrev_b32_e32 v182, 16, v222
	v_and_b32_e32 v183, 0xffff0000, v222
	v_lshlrev_b32_e32 v222, 16, v223
	v_and_b32_e32 v223, 0xffff0000, v223
	v_pk_mul_f32 v[52:53], v[52:53], v[180:181]
	v_pk_mul_f32 v[54:55], v[54:55], v[220:221]
	v_pk_mul_f32 v[182:183], v[48:49], v[182:183]
	v_pk_mul_f32 v[222:223], v[50:51], v[222:223]
	v_cvt_pk_bf16_f32 v48, v52, v53
	v_cvt_pk_bf16_f32 v49, v54, v55
	v_cvt_pk_bf16_f32 v50, v182, v183
	v_cvt_pk_bf16_f32 v51, v222, v223
	global_store_dwordx4 v[178:179], v[48:51], off offset:256
	s_waitcnt vmcnt(15)
	v_lshlrev_b32_e32 v180, 16, v224
	v_and_b32_e32 v181, 0xffff0000, v224
	v_lshlrev_b32_e32 v224, 16, v225
	v_and_b32_e32 v225, 0xffff0000, v225
	v_lshlrev_b32_e32 v182, 16, v226
	v_and_b32_e32 v183, 0xffff0000, v226
	v_lshlrev_b32_e32 v226, 16, v227
	v_and_b32_e32 v227, 0xffff0000, v227
	v_pk_mul_f32 v[44:45], v[44:45], v[180:181]
	v_pk_mul_f32 v[46:47], v[46:47], v[224:225]
	v_pk_mul_f32 v[182:183], v[40:41], v[182:183]
	v_pk_mul_f32 v[226:227], v[42:43], v[226:227]
	v_cvt_pk_bf16_f32 v40, v44, v45
	v_cvt_pk_bf16_f32 v41, v46, v47
	v_cvt_pk_bf16_f32 v42, v182, v183
	v_cvt_pk_bf16_f32 v43, v226, v227
	s_mov_b32 s100, 0x48000
	v_lshl_add_u64 v[178:179], v[172:173], 0, s[100:101]
	global_store_dwordx4 v[178:179], v[40:43], off
	s_waitcnt vmcnt(15)
	v_lshlrev_b32_e32 v180, 16, v228
	v_and_b32_e32 v181, 0xffff0000, v228
	v_lshlrev_b32_e32 v228, 16, v229
	v_and_b32_e32 v229, 0xffff0000, v229
	v_lshlrev_b32_e32 v182, 16, v230
	v_and_b32_e32 v183, 0xffff0000, v230
	v_lshlrev_b32_e32 v230, 16, v231
	v_and_b32_e32 v231, 0xffff0000, v231
	v_pk_mul_f32 v[36:37], v[36:37], v[180:181]
	v_pk_mul_f32 v[38:39], v[38:39], v[228:229]
	v_pk_mul_f32 v[182:183], v[32:33], v[182:183]
	v_pk_mul_f32 v[230:231], v[34:35], v[230:231]
	v_cvt_pk_bf16_f32 v32, v36, v37
	v_cvt_pk_bf16_f32 v33, v38, v39
	v_cvt_pk_bf16_f32 v34, v182, v183
	v_cvt_pk_bf16_f32 v35, v230, v231
	global_store_dwordx4 v[178:179], v[32:35], off offset:256
	s_waitcnt vmcnt(15)
	v_lshlrev_b32_e32 v180, 16, v232
	v_and_b32_e32 v181, 0xffff0000, v232
	v_lshlrev_b32_e32 v232, 16, v233
	v_and_b32_e32 v233, 0xffff0000, v233
	v_lshlrev_b32_e32 v182, 16, v234
	v_and_b32_e32 v183, 0xffff0000, v234
	v_lshlrev_b32_e32 v234, 16, v235
	v_and_b32_e32 v235, 0xffff0000, v235
	v_pk_mul_f32 v[28:29], v[28:29], v[180:181]
	v_pk_mul_f32 v[30:31], v[30:31], v[232:233]
	v_pk_mul_f32 v[182:183], v[24:25], v[182:183]
	v_pk_mul_f32 v[234:235], v[26:27], v[234:235]
	v_cvt_pk_bf16_f32 v24, v28, v29
	v_cvt_pk_bf16_f32 v25, v30, v31
	v_cvt_pk_bf16_f32 v26, v182, v183
	v_cvt_pk_bf16_f32 v27, v234, v235
	s_mov_b32 s100, 0x50000
	v_lshl_add_u64 v[178:179], v[172:173], 0, s[100:101]
	global_store_dwordx4 v[178:179], v[24:27], off
	s_waitcnt vmcnt(15)
	v_lshlrev_b32_e32 v180, 16, v236
	v_and_b32_e32 v181, 0xffff0000, v236
	v_lshlrev_b32_e32 v236, 16, v237
	v_and_b32_e32 v237, 0xffff0000, v237
	v_lshlrev_b32_e32 v182, 16, v238
	v_and_b32_e32 v183, 0xffff0000, v238
	v_lshlrev_b32_e32 v238, 16, v239
	v_and_b32_e32 v239, 0xffff0000, v239
	v_pk_mul_f32 v[20:21], v[20:21], v[180:181]
	v_pk_mul_f32 v[22:23], v[22:23], v[236:237]
	v_pk_mul_f32 v[182:183], v[16:17], v[182:183]
	v_pk_mul_f32 v[238:239], v[18:19], v[238:239]
	v_cvt_pk_bf16_f32 v16, v20, v21
	v_cvt_pk_bf16_f32 v17, v22, v23
	v_cvt_pk_bf16_f32 v18, v182, v183
	v_cvt_pk_bf16_f32 v19, v238, v239
	global_store_dwordx4 v[178:179], v[16:19], off offset:256
	s_waitcnt vmcnt(15)
	v_lshlrev_b32_e32 v180, 16, v240
	v_and_b32_e32 v181, 0xffff0000, v240
	v_lshlrev_b32_e32 v240, 16, v241
	v_and_b32_e32 v241, 0xffff0000, v241
	v_lshlrev_b32_e32 v182, 16, v242
	v_and_b32_e32 v183, 0xffff0000, v242
	v_lshlrev_b32_e32 v242, 16, v243
	v_and_b32_e32 v243, 0xffff0000, v243
	v_pk_mul_f32 v[12:13], v[12:13], v[180:181]
	v_pk_mul_f32 v[14:15], v[14:15], v[240:241]
	v_pk_mul_f32 v[182:183], v[8:9], v[182:183]
	v_pk_mul_f32 v[242:243], v[10:11], v[242:243]
	v_cvt_pk_bf16_f32 v8, v12, v13
	v_cvt_pk_bf16_f32 v9, v14, v15
	v_cvt_pk_bf16_f32 v10, v182, v183
	v_cvt_pk_bf16_f32 v11, v242, v243
	s_mov_b32 s100, 0x58000
	v_lshl_add_u64 v[178:179], v[172:173], 0, s[100:101]
	global_store_dwordx4 v[178:179], v[8:11], off
	s_waitcnt vmcnt(14)
	v_lshlrev_b32_e32 v180, 16, v184
	v_and_b32_e32 v181, 0xffff0000, v184
	v_lshlrev_b32_e32 v184, 16, v185
	v_and_b32_e32 v185, 0xffff0000, v185
	v_lshlrev_b32_e32 v182, 16, v186
	v_and_b32_e32 v183, 0xffff0000, v186
	v_lshlrev_b32_e32 v186, 16, v187
	v_and_b32_e32 v187, 0xffff0000, v187
	v_pk_mul_f32 v[4:5], v[4:5], v[180:181]
	v_pk_mul_f32 v[6:7], v[6:7], v[184:185]
	v_pk_mul_f32 v[182:183], v[0:1], v[182:183]
	v_pk_mul_f32 v[186:187], v[2:3], v[186:187]
	v_cvt_pk_bf16_f32 v0, v4, v5
	v_cvt_pk_bf16_f32 v1, v6, v7
	v_cvt_pk_bf16_f32 v2, v182, v183
	v_cvt_pk_bf16_f32 v3, v186, v187
	global_store_dwordx4 v[178:179], v[0:3], off offset:256
	s_cbranch_vccnz .LBB0_1471
	s_andn2_b64 vcc, exec, s[24:25]
	s_cbranch_vccnz .LBB0_1470
	s_barrier
	s_branch .LBB0_1470

.LBB0_1516:
	s_ashr_i32 s47, s46, 31
	s_lshl_b64 s[46:47], s[46:47], 8
	v_mov_b32_e32 v144, v148
	v_mov_b32_e32 v169, v149
	s_add_u32 s46, s46, s88
	s_addc_u32 s47, s47, s69
	v_ashrrev_i32_e32 v145, 31, v144
	v_lshl_add_u64 v[146:147], s[46:47], 0, v[144:145]
	s_lshl_b32 s46, s77, 8
	s_or_b32 s46, s46, s89
	v_lshl_add_u32 v144, v169, 3, s46
	v_lshlrev_b64 v[170:171], 12, v[146:147]
	v_ashrrev_i32_e32 v145, 31, v144
	v_lshl_add_u64 v[170:171], s[8:9], 0, v[170:171]
	v_lshlrev_b64 v[144:145], 1, v[144:145]
	v_lshlrev_b64 v[174:175], 11, v[146:147]
	v_lshl_add_u64 v[182:183], v[170:171], 0, v[144:145]
	v_lshl_add_u64 v[174:175], s[86:87], 0, v[174:175]
	v_lshl_add_u64 v[184:185], v[174:175], 0, v[144:145]
	s_mov_b64 s[46:47], 0x90
	s_and_b64 vcc, exec, s[6:7]
	s_mov_b64 s[6:7], -1
	v_mov_b32_e32 v170, v182
	v_mov_b32_e32 v171, v183
	v_mov_b32_e32 v172, v184
	v_mov_b32_e32 v173, v185
	s_mov_b32 s101, 0
	global_load_dwordx4 v[188:191], v[170:171], off offset:2048
	global_load_dwordx4 v[192:195], v[172:173], off
	global_load_dwordx4 v[196:199], v[170:171], off offset:2304
	global_load_dwordx4 v[200:203], v[172:173], off offset:256
	s_mov_b32 s100, 0x10000
	v_lshl_add_u64 v[174:175], v[170:171], 0, s[100:101]
	global_load_dwordx4 v[204:207], v[174:175], off offset:2048
	s_mov_b32 s100, 0x8000
	v_lshl_add_u64 v[176:177], v[172:173], 0, s[100:101]
	global_load_dwordx4 v[208:211], v[176:177], off
	s_mov_b32 s100, 0x10000
	v_lshl_add_u64 v[174:175], v[170:171], 0, s[100:101]
	global_load_dwordx4 v[212:215], v[174:175], off offset:2304
	s_mov_b32 s100, 0x8000
	v_lshl_add_u64 v[176:177], v[172:173], 0, s[100:101]
	global_load_dwordx4 v[216:219], v[176:177], off offset:256
	s_mov_b32 s100, 0x20000
	v_lshl_add_u64 v[174:175], v[170:171], 0, s[100:101]
	global_load_dwordx4 v[220:223], v[174:175], off offset:2048
	s_mov_b32 s100, 0x10000
	v_lshl_add_u64 v[176:177], v[172:173], 0, s[100:101]
	global_load_dwordx4 v[224:227], v[176:177], off
	s_mov_b32 s100, 0x20000
	v_lshl_add_u64 v[174:175], v[170:171], 0, s[100:101]
	global_load_dwordx4 v[228:231], v[174:175], off offset:2304
	s_mov_b32 s100, 0x10000
	v_lshl_add_u64 v[176:177], v[172:173], 0, s[100:101]
	global_load_dwordx4 v[232:235], v[176:177], off offset:256
	s_mov_b32 s100, 0x30000
	v_lshl_add_u64 v[174:175], v[170:171], 0, s[100:101]
	global_load_dwordx4 v[236:239], v[174:175], off offset:2048
	s_mov_b32 s100, 0x18000
	v_lshl_add_u64 v[176:177], v[172:173], 0, s[100:101]
	global_load_dwordx4 v[240:243], v[176:177], off
	s_waitcnt vmcnt(12)
	v_lshlrev_b32_e32 v180, 16, v188
	v_and_b32_e32 v181, 0xffff0000, v188
	v_lshlrev_b32_e32 v188, 16, v189
	v_and_b32_e32 v189, 0xffff0000, v189
	v_lshlrev_b32_e32 v182, 16, v190
	v_and_b32_e32 v183, 0xffff0000, v190
	v_lshlrev_b32_e32 v190, 16, v191
	v_and_b32_e32 v191, 0xffff0000, v191
	v_lshlrev_b32_e32 v184, 16, v192
	v_and_b32_e32 v185, 0xffff0000, v192
	v_lshlrev_b32_e32 v192, 16, v193
	v_and_b32_e32 v193, 0xffff0000, v193
	v_lshlrev_b32_e32 v186, 16, v194
	v_and_b32_e32 v187, 0xffff0000, v194
	v_lshlrev_b32_e32 v194, 16, v195
	v_and_b32_e32 v195, 0xffff0000, v195
	v_pk_fma_f32 v[124:125], v[124:125], v[180:181], v[184:185]
	v_pk_fma_f32 v[126:127], v[126:127], v[188:189], v[192:193]
	v_pk_fma_f32 v[182:183], v[120:121], v[182:183], v[186:187]
	v_pk_fma_f32 v[190:191], v[122:123], v[190:191], v[194:195]
	v_cvt_pk_bf16_f32 v120, v124, v125
	v_cvt_pk_bf16_f32 v121, v126, v127
	v_cvt_pk_bf16_f32 v122, v182, v183
	v_cvt_pk_bf16_f32 v123, v190, v191
	global_store_dwordx4 v[172:173], v[120:123], off
	s_mov_b32 s100, 0x30000
	v_lshl_add_u64 v[174:175], v[170:171], 0, s[100:101]
	global_load_dwordx4 v[188:191], v[174:175], off offset:2304
	s_mov_b32 s100, 0x18000
	v_lshl_add_u64 v[176:177], v[172:173], 0, s[100:101]
	global_load_dwordx4 v[192:195], v[176:177], off offset:256
	s_waitcnt vmcnt(13)
	v_lshlrev_b32_e32 v180, 16, v196
	v_and_b32_e32 v181, 0xffff0000, v196
	v_lshlrev_b32_e32 v196, 16, v197
	v_and_b32_e32 v197, 0xffff0000, v197
	v_lshlrev_b32_e32 v182, 16, v198
	v_and_b32_e32 v183, 0xffff0000, v198
	v_lshlrev_b32_e32 v198, 16, v199
	v_and_b32_e32 v199, 0xffff0000, v199
	v_lshlrev_b32_e32 v184, 16, v200
	v_and_b32_e32 v185, 0xffff0000, v200
	v_lshlrev_b32_e32 v200, 16, v201
	v_and_b32_e32 v201, 0xffff0000, v201
	v_lshlrev_b32_e32 v186, 16, v202
	v_and_b32_e32 v187, 0xffff0000, v202
	v_lshlrev_b32_e32 v202, 16, v203
	v_and_b32_e32 v203, 0xffff0000, v203
	v_pk_fma_f32 v[116:117], v[116:117], v[180:181], v[184:185]
	v_pk_fma_f32 v[118:119], v[118:119], v[196:197], v[200:201]
	v_pk_fma_f32 v[182:183], v[112:113], v[182:183], v[186:187]
	v_pk_fma_f32 v[198:199], v[114:115], v[198:199], v[202:203]
	v_cvt_pk_bf16_f32 v112, v116, v117
	v_cvt_pk_bf16_f32 v113, v118, v119
	v_cvt_pk_bf16_f32 v114, v182, v183
	v_cvt_pk_bf16_f32 v115, v198, v199
	global_store_dwordx4 v[172:173], v[112:115], off offset:256
	s_mov_b32 s100, 0x80000
	v_lshl_add_u64 v[174:175], v[170:171], 0, s[100:101]
	global_load_dwordx4 v[196:199], v[174:175], off offset:2048
	s_mov_b32 s100, 0x40000
	v_lshl_add_u64 v[176:177], v[172:173], 0, s[100:101]
	global_load_dwordx4 v[200:203], v[176:177], off
	s_waitcnt vmcnt(14)
	v_lshlrev_b32_e32 v180, 16, v204
	v_and_b32_e32 v181, 0xffff0000, v204
	v_lshlrev_b32_e32 v204, 16, v205
	v_and_b32_e32 v205, 0xffff0000, v205
	v_lshlrev_b32_e32 v182, 16, v206
	v_and_b32_e32 v183, 0xffff0000, v206
	v_lshlrev_b32_e32 v206, 16, v207
	v_and_b32_e32 v207, 0xffff0000, v207
	v_lshlrev_b32_e32 v184, 16, v208
	v_and_b32_e32 v185, 0xffff0000, v208
	v_lshlrev_b32_e32 v208, 16, v209
	v_and_b32_e32 v209, 0xffff0000, v209
	v_lshlrev_b32_e32 v186, 16, v210
	v_and_b32_e32 v187, 0xffff0000, v210
	v_lshlrev_b32_e32 v210, 16, v211
	v_and_b32_e32 v211, 0xffff0000, v211
	v_pk_fma_f32 v[108:109], v[108:109], v[180:181], v[184:185]
	v_pk_fma_f32 v[110:111], v[110:111], v[204:205], v[208:209]
	v_pk_fma_f32 v[182:183], v[104:105], v[182:183], v[186:187]
	v_pk_fma_f32 v[206:207], v[106:107], v[206:207], v[210:211]
	v_cvt_pk_bf16_f32 v104, v108, v109
	v_cvt_pk_bf16_f32 v105, v110, v111
	v_cvt_pk_bf16_f32 v106, v182, v183
	v_cvt_pk_bf16_f32 v107, v206, v207
	s_mov_b32 s100, 0x8000
	v_lshl_add_u64 v[178:179], v[172:173], 0, s[100:101]
	global_store_dwordx4 v[178:179], v[104:107], off
	s_mov_b32 s100, 0x80000
	v_lshl_add_u64 v[174:175], v[170:171], 0, s[100:101]
	global_load_dwordx4 v[204:207], v[174:175], off offset:2304
	s_mov_b32 s100, 0x40000
	v_lshl_add_u64 v[176:177], v[172:173], 0, s[100:101]
	global_load_dwordx4 v[208:211], v[176:177], off offset:256
	s_waitcnt vmcnt(15)
	v_lshlrev_b32_e32 v180, 16, v212
	v_and_b32_e32 v181, 0xffff0000, v212
	v_lshlrev_b32_e32 v212, 16, v213
	v_and_b32_e32 v213, 0xffff0000, v213
	v_lshlrev_b32_e32 v182, 16, v214
	v_and_b32_e32 v183, 0xffff0000, v214
	v_lshlrev_b32_e32 v214, 16, v215
	v_and_b32_e32 v215, 0xffff0000, v215
	v_lshlrev_b32_e32 v184, 16, v216
	v_and_b32_e32 v185, 0xffff0000, v216
	v_lshlrev_b32_e32 v216, 16, v217
	v_and_b32_e32 v217, 0xffff0000, v217
	v_lshlrev_b32_e32 v186, 16, v218
	v_and_b32_e32 v187, 0xffff0000, v218
	v_lshlrev_b32_e32 v218, 16, v219
	v_and_b32_e32 v219, 0xffff0000, v219
	v_pk_fma_f32 v[100:101], v[100:101], v[180:181], v[184:185]
	v_pk_fma_f32 v[102:103], v[102:103], v[212:213], v[216:217]
	v_pk_fma_f32 v[182:183], v[96:97], v[182:183], v[186:187]
	v_pk_fma_f32 v[214:215], v[98:99], v[214:215], v[218:219]
	v_cvt_pk_bf16_f32 v96, v100, v101
	v_cvt_pk_bf16_f32 v97, v102, v103
	v_cvt_pk_bf16_f32 v98, v182, v183
	v_cvt_pk_bf16_f32 v99, v214, v215
	global_store_dwordx4 v[178:179], v[96:99], off offset:256
	s_mov_b32 s100, 0x90000
	v_lshl_add_u64 v[174:175], v[170:171], 0, s[100:101]
	global_load_dwordx4 v[212:215], v[174:175], off offset:2048
	s_mov_b32 s100, 0x48000
	v_lshl_add_u64 v[176:177], v[172:173], 0, s[100:101]
	global_load_dwordx4 v[216:219], v[176:177], off
	s_waitcnt vmcnt(16)
	v_lshlrev_b32_e32 v180, 16, v220
	v_and_b32_e32 v181, 0xffff0000, v220
	v_lshlrev_b32_e32 v220, 16, v221
	v_and_b32_e32 v221, 0xffff0000, v221
	v_lshlrev_b32_e32 v182, 16, v222
	v_and_b32_e32 v183, 0xffff0000, v222
	v_lshlrev_b32_e32 v222, 16, v223
	v_and_b32_e32 v223, 0xffff0000, v223
	v_lshlrev_b32_e32 v184, 16, v224
	v_and_b32_e32 v185, 0xffff0000, v224
	v_lshlrev_b32_e32 v224, 16, v225
	v_and_b32_e32 v225, 0xffff0000, v225
	v_lshlrev_b32_e32 v186, 16, v226
	v_and_b32_e32 v187, 0xffff0000, v226
	v_lshlrev_b32_e32 v226, 16, v227
	v_and_b32_e32 v227, 0xffff0000, v227
	v_pk_fma_f32 v[92:93], v[92:93], v[180:181], v[184:185]
	v_pk_fma_f32 v[94:95], v[94:95], v[220:221], v[224:225]
	v_pk_fma_f32 v[182:183], v[88:89], v[182:183], v[186:187]
	v_pk_fma_f32 v[222:223], v[90:91], v[222:223], v[226:227]
	v_cvt_pk_bf16_f32 v88, v92, v93
	v_cvt_pk_bf16_f32 v89, v94, v95
	v_cvt_pk_bf16_f32 v90, v182, v183
	v_cvt_pk_bf16_f32 v91, v222, v223
	s_mov_b32 s100, 0x10000
	v_lshl_add_u64 v[178:179], v[172:173], 0, s[100:101]
	global_store_dwordx4 v[178:179], v[88:91], off
	s_mov_b32 s100, 0x90000
	v_lshl_add_u64 v[174:175], v[170:171], 0, s[100:101]
	global_load_dwordx4 v[220:223], v[174:175], off offset:2304
	s_mov_b32 s100, 0x48000
	v_lshl_add_u64 v[176:177], v[172:173], 0, s[100:101]
	global_load_dwordx4 v[224:227], v[176:177], off offset:256
	s_waitcnt vmcnt(17)
	v_lshlrev_b32_e32 v180, 16, v228
	v_and_b32_e32 v181, 0xffff0000, v228
	v_lshlrev_b32_e32 v228, 16, v229
	v_and_b32_e32 v229, 0xffff0000, v229
	v_lshlrev_b32_e32 v182, 16, v230
	v_and_b32_e32 v183, 0xffff0000, v230
	v_lshlrev_b32_e32 v230, 16, v231
	v_and_b32_e32 v231, 0xffff0000, v231
	v_lshlrev_b32_e32 v184, 16, v232
	v_and_b32_e32 v185, 0xffff0000, v232
	v_lshlrev_b32_e32 v232, 16, v233
	v_and_b32_e32 v233, 0xffff0000, v233
	v_lshlrev_b32_e32 v186, 16, v234
	v_and_b32_e32 v187, 0xffff0000, v234
	v_lshlrev_b32_e32 v234, 16, v235
	v_and_b32_e32 v235, 0xffff0000, v235
	v_pk_fma_f32 v[84:85], v[84:85], v[180:181], v[184:185]
	v_pk_fma_f32 v[86:87], v[86:87], v[228:229], v[232:233]
	v_pk_fma_f32 v[182:183], v[80:81], v[182:183], v[186:187]
	v_pk_fma_f32 v[230:231], v[82:83], v[230:231], v[234:235]
	v_cvt_pk_bf16_f32 v80, v84, v85
	v_cvt_pk_bf16_f32 v81, v86, v87
	v_cvt_pk_bf16_f32 v82, v182, v183
	v_cvt_pk_bf16_f32 v83, v230, v231
	global_store_dwordx4 v[178:179], v[80:83], off offset:256
	s_mov_b32 s100, 0xa0000
	v_lshl_add_u64 v[174:175], v[170:171], 0, s[100:101]
	global_load_dwordx4 v[228:231], v[174:175], off offset:2048
	s_mov_b32 s100, 0x50000
	v_lshl_add_u64 v[176:177], v[172:173], 0, s[100:101]
	global_load_dwordx4 v[232:235], v[176:177], off
	s_waitcnt vmcnt(18)
	v_lshlrev_b32_e32 v180, 16, v236
	v_and_b32_e32 v181, 0xffff0000, v236
	v_lshlrev_b32_e32 v236, 16, v237
	v_and_b32_e32 v237, 0xffff0000, v237
	v_lshlrev_b32_e32 v182, 16, v238
	v_and_b32_e32 v183, 0xffff0000, v238
	v_lshlrev_b32_e32 v238, 16, v239
	v_and_b32_e32 v239, 0xffff0000, v239
	v_lshlrev_b32_e32 v184, 16, v240
	v_and_b32_e32 v185, 0xffff0000, v240
	v_lshlrev_b32_e32 v240, 16, v241
	v_and_b32_e32 v241, 0xffff0000, v241
	v_lshlrev_b32_e32 v186, 16, v242
	v_and_b32_e32 v187, 0xffff0000, v242
	v_lshlrev_b32_e32 v242, 16, v243
	v_and_b32_e32 v243, 0xffff0000, v243
	v_pk_fma_f32 v[76:77], v[76:77], v[180:181], v[184:185]
	v_pk_fma_f32 v[78:79], v[78:79], v[236:237], v[240:241]
	v_pk_fma_f32 v[182:183], v[72:73], v[182:183], v[186:187]
	v_pk_fma_f32 v[238:239], v[74:75], v[238:239], v[242:243]
	v_cvt_pk_bf16_f32 v72, v76, v77
	v_cvt_pk_bf16_f32 v73, v78, v79
	v_cvt_pk_bf16_f32 v74, v182, v183
	v_cvt_pk_bf16_f32 v75, v238, v239
	s_mov_b32 s100, 0x18000
	v_lshl_add_u64 v[178:179], v[172:173], 0, s[100:101]
	global_store_dwordx4 v[178:179], v[72:75], off
	s_mov_b32 s100, 0xa0000
	v_lshl_add_u64 v[174:175], v[170:171], 0, s[100:101]
	global_load_dwordx4 v[236:239], v[174:175], off offset:2304
	s_mov_b32 s100, 0x50000
	v_lshl_add_u64 v[176:177], v[172:173], 0, s[100:101]
	global_load_dwordx4 v[240:243], v[176:177], off offset:256
	s_waitcnt vmcnt(18)
	v_lshlrev_b32_e32 v180, 16, v188
	v_and_b32_e32 v181, 0xffff0000, v188
	v_lshlrev_b32_e32 v188, 16, v189
	v_and_b32_e32 v189, 0xffff0000, v189
	v_lshlrev_b32_e32 v182, 16, v190
	v_and_b32_e32 v183, 0xffff0000, v190
	v_lshlrev_b32_e32 v190, 16, v191
	v_and_b32_e32 v191, 0xffff0000, v191
	v_lshlrev_b32_e32 v184, 16, v192
	v_and_b32_e32 v185, 0xffff0000, v192
	v_lshlrev_b32_e32 v192, 16, v193
	v_and_b32_e32 v193, 0xffff0000, v193
	v_lshlrev_b32_e32 v186, 16, v194
	v_and_b32_e32 v187, 0xffff0000, v194
	v_lshlrev_b32_e32 v194, 16, v195
	v_and_b32_e32 v195, 0xffff0000, v195
	v_pk_fma_f32 v[68:69], v[68:69], v[180:181], v[184:185]
	v_pk_fma_f32 v[70:71], v[70:71], v[188:189], v[192:193]
	v_pk_fma_f32 v[182:183], v[64:65], v[182:183], v[186:187]
	v_pk_fma_f32 v[190:191], v[66:67], v[190:191], v[194:195]
	v_cvt_pk_bf16_f32 v64, v68, v69
	v_cvt_pk_bf16_f32 v65, v70, v71
	v_cvt_pk_bf16_f32 v66, v182, v183
	v_cvt_pk_bf16_f32 v67, v190, v191
	global_store_dwordx4 v[178:179], v[64:67], off offset:256
	s_mov_b32 s100, 0xb0000
	v_lshl_add_u64 v[174:175], v[170:171], 0, s[100:101]
	global_load_dwordx4 v[188:191], v[174:175], off offset:2048
	s_mov_b32 s100, 0x58000
	v_lshl_add_u64 v[176:177], v[172:173], 0, s[100:101]
	global_load_dwordx4 v[192:195], v[176:177], off
	s_waitcnt vmcnt(18)
	v_lshlrev_b32_e32 v180, 16, v196
	v_and_b32_e32 v181, 0xffff0000, v196
	v_lshlrev_b32_e32 v196, 16, v197
	v_and_b32_e32 v197, 0xffff0000, v197
	v_lshlrev_b32_e32 v182, 16, v198
	v_and_b32_e32 v183, 0xffff0000, v198
	v_lshlrev_b32_e32 v198, 16, v199
	v_and_b32_e32 v199, 0xffff0000, v199
	v_lshlrev_b32_e32 v184, 16, v200
	v_and_b32_e32 v185, 0xffff0000, v200
	v_lshlrev_b32_e32 v200, 16, v201
	v_and_b32_e32 v201, 0xffff0000, v201
	v_lshlrev_b32_e32 v186, 16, v202
	v_and_b32_e32 v187, 0xffff0000, v202
	v_lshlrev_b32_e32 v202, 16, v203
	v_and_b32_e32 v203, 0xffff0000, v203
	v_pk_fma_f32 v[60:61], v[60:61], v[180:181], v[184:185]
	v_pk_fma_f32 v[62:63], v[62:63], v[196:197], v[200:201]
	v_pk_fma_f32 v[182:183], v[56:57], v[182:183], v[186:187]
	v_pk_fma_f32 v[198:199], v[58:59], v[198:199], v[202:203]
	v_cvt_pk_bf16_f32 v56, v60, v61
	v_cvt_pk_bf16_f32 v57, v62, v63
	v_cvt_pk_bf16_f32 v58, v182, v183
	v_cvt_pk_bf16_f32 v59, v198, v199
	s_mov_b32 s100, 0x40000
	v_lshl_add_u64 v[178:179], v[172:173], 0, s[100:101]
	global_store_dwordx4 v[178:179], v[56:59], off
	s_mov_b32 s100, 0xb0000
	v_lshl_add_u64 v[174:175], v[170:171], 0, s[100:101]
	global_load_dwordx4 v[196:199], v[174:175], off offset:2304
	s_mov_b32 s100, 0x58000
	v_lshl_add_u64 v[176:177], v[172:173], 0, s[100:101]
	global_load_dwordx4 v[200:203], v[176:177], off offset:256
	s_waitcnt vmcnt(18)
	v_lshlrev_b32_e32 v180, 16, v204
	v_and_b32_e32 v181, 0xffff0000, v204
	v_lshlrev_b32_e32 v204, 16, v205
	v_and_b32_e32 v205, 0xffff0000, v205
	v_lshlrev_b32_e32 v182, 16, v206
	v_and_b32_e32 v183, 0xffff0000, v206
	v_lshlrev_b32_e32 v206, 16, v207
	v_and_b32_e32 v207, 0xffff0000, v207
	v_lshlrev_b32_e32 v184, 16, v208
	v_and_b32_e32 v185, 0xffff0000, v208
	v_lshlrev_b32_e32 v208, 16, v209
	v_and_b32_e32 v209, 0xffff0000, v209
	v_lshlrev_b32_e32 v186, 16, v210
	v_and_b32_e32 v187, 0xffff0000, v210
	v_lshlrev_b32_e32 v210, 16, v211
	v_and_b32_e32 v211, 0xffff0000, v211
	v_pk_fma_f32 v[52:53], v[52:53], v[180:181], v[184:185]
	v_pk_fma_f32 v[54:55], v[54:55], v[204:205], v[208:209]
	v_pk_fma_f32 v[182:183], v[48:49], v[182:183], v[186:187]
	v_pk_fma_f32 v[206:207], v[50:51], v[206:207], v[210:211]
	v_cvt_pk_bf16_f32 v48, v52, v53
	v_cvt_pk_bf16_f32 v49, v54, v55
	v_cvt_pk_bf16_f32 v50, v182, v183
	v_cvt_pk_bf16_f32 v51, v206, v207
	global_store_dwordx4 v[178:179], v[48:51], off offset:256
	s_waitcnt vmcnt(16)
	v_lshlrev_b32_e32 v180, 16, v212
	v_and_b32_e32 v181, 0xffff0000, v212
	v_lshlrev_b32_e32 v212, 16, v213
	v_and_b32_e32 v213, 0xffff0000, v213
	v_lshlrev_b32_e32 v182, 16, v214
	v_and_b32_e32 v183, 0xffff0000, v214
	v_lshlrev_b32_e32 v214, 16, v215
	v_and_b32_e32 v215, 0xffff0000, v215
	v_lshlrev_b32_e32 v184, 16, v216
	v_and_b32_e32 v185, 0xffff0000, v216
	v_lshlrev_b32_e32 v216, 16, v217
	v_and_b32_e32 v217, 0xffff0000, v217
	v_lshlrev_b32_e32 v186, 16, v218
	v_and_b32_e32 v187, 0xffff0000, v218
	v_lshlrev_b32_e32 v218, 16, v219
	v_and_b32_e32 v219, 0xffff0000, v219
	v_pk_fma_f32 v[44:45], v[44:45], v[180:181], v[184:185]
	v_pk_fma_f32 v[46:47], v[46:47], v[212:213], v[216:217]
	v_pk_fma_f32 v[182:183], v[40:41], v[182:183], v[186:187]
	v_pk_fma_f32 v[214:215], v[42:43], v[214:215], v[218:219]
	v_cvt_pk_bf16_f32 v40, v44, v45
	v_cvt_pk_bf16_f32 v41, v46, v47
	v_cvt_pk_bf16_f32 v42, v182, v183
	v_cvt_pk_bf16_f32 v43, v214, v215
	s_mov_b32 s100, 0x48000
	v_lshl_add_u64 v[178:179], v[172:173], 0, s[100:101]
	global_store_dwordx4 v[178:179], v[40:43], off
	s_waitcnt vmcnt(14)
	v_lshlrev_b32_e32 v180, 16, v220
	v_and_b32_e32 v181, 0xffff0000, v220
	v_lshlrev_b32_e32 v220, 16, v221
	v_and_b32_e32 v221, 0xffff0000, v221
	v_lshlrev_b32_e32 v182, 16, v222
	v_and_b32_e32 v183, 0xffff0000, v222
	v_lshlrev_b32_e32 v222, 16, v223
	v_and_b32_e32 v223, 0xffff0000, v223
	v_lshlrev_b32_e32 v184, 16, v224
	v_and_b32_e32 v185, 0xffff0000, v224
	v_lshlrev_b32_e32 v224, 16, v225
	v_and_b32_e32 v225, 0xffff0000, v225
	v_lshlrev_b32_e32 v186, 16, v226
	v_and_b32_e32 v187, 0xffff0000, v226
	v_lshlrev_b32_e32 v226, 16, v227
	v_and_b32_e32 v227, 0xffff0000, v227
	v_pk_fma_f32 v[36:37], v[36:37], v[180:181], v[184:185]
	v_pk_fma_f32 v[38:39], v[38:39], v[220:221], v[224:225]
	v_pk_fma_f32 v[182:183], v[32:33], v[182:183], v[186:187]
	v_pk_fma_f32 v[222:223], v[34:35], v[222:223], v[226:227]
	v_cvt_pk_bf16_f32 v32, v36, v37
	v_cvt_pk_bf16_f32 v33, v38, v39
	v_cvt_pk_bf16_f32 v34, v182, v183
	v_cvt_pk_bf16_f32 v35, v222, v223
	global_store_dwordx4 v[178:179], v[32:35], off offset:256
	s_waitcnt vmcnt(12)
	v_lshlrev_b32_e32 v180, 16, v228
	v_and_b32_e32 v181, 0xffff0000, v228
	v_lshlrev_b32_e32 v228, 16, v229
	v_and_b32_e32 v229, 0xffff0000, v229
	v_lshlrev_b32_e32 v182, 16, v230
	v_and_b32_e32 v183, 0xffff0000, v230
	v_lshlrev_b32_e32 v230, 16, v231
	v_and_b32_e32 v231, 0xffff0000, v231
	v_lshlrev_b32_e32 v184, 16, v232
	v_and_b32_e32 v185, 0xffff0000, v232
	v_lshlrev_b32_e32 v232, 16, v233
	v_and_b32_e32 v233, 0xffff0000, v233
	v_lshlrev_b32_e32 v186, 16, v234
	v_and_b32_e32 v187, 0xffff0000, v234
	v_lshlrev_b32_e32 v234, 16, v235
	v_and_b32_e32 v235, 0xffff0000, v235
	v_pk_fma_f32 v[28:29], v[28:29], v[180:181], v[184:185]
	v_pk_fma_f32 v[30:31], v[30:31], v[228:229], v[232:233]
	v_pk_fma_f32 v[182:183], v[24:25], v[182:183], v[186:187]
	v_pk_fma_f32 v[230:231], v[26:27], v[230:231], v[234:235]
	v_cvt_pk_bf16_f32 v24, v28, v29
	v_cvt_pk_bf16_f32 v25, v30, v31
	v_cvt_pk_bf16_f32 v26, v182, v183
	v_cvt_pk_bf16_f32 v27, v230, v231
	s_mov_b32 s100, 0x50000
	v_lshl_add_u64 v[178:179], v[172:173], 0, s[100:101]
	global_store_dwordx4 v[178:179], v[24:27], off
	s_waitcnt vmcnt(10)
	v_lshlrev_b32_e32 v180, 16, v236
	v_and_b32_e32 v181, 0xffff0000, v236
	v_lshlrev_b32_e32 v236, 16, v237
	v_and_b32_e32 v237, 0xffff0000, v237
	v_lshlrev_b32_e32 v182, 16, v238
	v_and_b32_e32 v183, 0xffff0000, v238
	v_lshlrev_b32_e32 v238, 16, v239
	v_and_b32_e32 v239, 0xffff0000, v239
	v_lshlrev_b32_e32 v184, 16, v240
	v_and_b32_e32 v185, 0xffff0000, v240
	v_lshlrev_b32_e32 v240, 16, v241
	v_and_b32_e32 v241, 0xffff0000, v241
	v_lshlrev_b32_e32 v186, 16, v242
	v_and_b32_e32 v187, 0xffff0000, v242
	v_lshlrev_b32_e32 v242, 16, v243
	v_and_b32_e32 v243, 0xffff0000, v243
	v_pk_fma_f32 v[20:21], v[20:21], v[180:181], v[184:185]
	v_pk_fma_f32 v[22:23], v[22:23], v[236:237], v[240:241]
	v_pk_fma_f32 v[182:183], v[16:17], v[182:183], v[186:187]
	v_pk_fma_f32 v[238:239], v[18:19], v[238:239], v[242:243]
	v_cvt_pk_bf16_f32 v16, v20, v21
	v_cvt_pk_bf16_f32 v17, v22, v23
	v_cvt_pk_bf16_f32 v18, v182, v183
	v_cvt_pk_bf16_f32 v19, v238, v239
	global_store_dwordx4 v[178:179], v[16:19], off offset:256
	s_waitcnt vmcnt(8)
	v_lshlrev_b32_e32 v180, 16, v188
	v_and_b32_e32 v181, 0xffff0000, v188
	v_lshlrev_b32_e32 v188, 16, v189
	v_and_b32_e32 v189, 0xffff0000, v189
	v_lshlrev_b32_e32 v182, 16, v190
	v_and_b32_e32 v183, 0xffff0000, v190
	v_lshlrev_b32_e32 v190, 16, v191
	v_and_b32_e32 v191, 0xffff0000, v191
	v_lshlrev_b32_e32 v184, 16, v192
	v_and_b32_e32 v185, 0xffff0000, v192
	v_lshlrev_b32_e32 v192, 16, v193
	v_and_b32_e32 v193, 0xffff0000, v193
	v_lshlrev_b32_e32 v186, 16, v194
	v_and_b32_e32 v187, 0xffff0000, v194
	v_lshlrev_b32_e32 v194, 16, v195
	v_and_b32_e32 v195, 0xffff0000, v195
	v_pk_fma_f32 v[12:13], v[12:13], v[180:181], v[184:185]
	v_pk_fma_f32 v[14:15], v[14:15], v[188:189], v[192:193]
	v_pk_fma_f32 v[182:183], v[8:9], v[182:183], v[186:187]
	v_pk_fma_f32 v[190:191], v[10:11], v[190:191], v[194:195]
	v_cvt_pk_bf16_f32 v8, v12, v13
	v_cvt_pk_bf16_f32 v9, v14, v15
	v_cvt_pk_bf16_f32 v10, v182, v183
	v_cvt_pk_bf16_f32 v11, v190, v191
	s_mov_b32 s100, 0x58000
	v_lshl_add_u64 v[178:179], v[172:173], 0, s[100:101]
	global_store_dwordx4 v[178:179], v[8:11], off
	s_waitcnt vmcnt(6)
	v_lshlrev_b32_e32 v180, 16, v196
	v_and_b32_e32 v181, 0xffff0000, v196
	v_lshlrev_b32_e32 v196, 16, v197
	v_and_b32_e32 v197, 0xffff0000, v197
	v_lshlrev_b32_e32 v182, 16, v198
	v_and_b32_e32 v183, 0xffff0000, v198
	v_lshlrev_b32_e32 v198, 16, v199
	v_and_b32_e32 v199, 0xffff0000, v199
	v_lshlrev_b32_e32 v184, 16, v200
	v_and_b32_e32 v185, 0xffff0000, v200
	v_lshlrev_b32_e32 v200, 16, v201
	v_and_b32_e32 v201, 0xffff0000, v201
	v_lshlrev_b32_e32 v186, 16, v202
	v_and_b32_e32 v187, 0xffff0000, v202
	v_lshlrev_b32_e32 v202, 16, v203
	v_and_b32_e32 v203, 0xffff0000, v203
	v_pk_fma_f32 v[4:5], v[4:5], v[180:181], v[184:185]
	v_pk_fma_f32 v[6:7], v[6:7], v[196:197], v[200:201]
	v_pk_fma_f32 v[182:183], v[0:1], v[182:183], v[186:187]
	v_pk_fma_f32 v[198:199], v[2:3], v[198:199], v[202:203]
	v_cvt_pk_bf16_f32 v0, v4, v5
	v_cvt_pk_bf16_f32 v1, v6, v7
	v_cvt_pk_bf16_f32 v2, v182, v183
	v_cvt_pk_bf16_f32 v3, v198, v199
	global_store_dwordx4 v[178:179], v[0:3], off offset:256
	s_cbranch_vccnz .LBB0_1500
	s_andn2_b64 vcc, exec, s[18:19]
	s_cbranch_vccnz .LBB0_1499
	s_barrier
	s_branch .LBB0_1499
